# pass 1 OMIX stores: 8-byte stores paired into 16-byte write-through (sc1) stores via v_permlane16_swap
# speedup vs baseline: 1.0044x; 1.0044x over previous
; __device__ __forceinline__ unsigned pk2(float lo, float hi) { const f32x2cv v = {lo, hi}; const bf16x2cv b = __builtin_convertvector(v, bf16x2cv); return __builtin_bit_cast(unsigned, b); }
; template <int PASS>
; __device__ __forceinline__ void gla_unit(LAS unsigned char* lds, int ch, int h, const bf16* PROJ, const bf16* GT, bf16* STG, float* DECG, bf16* OMIX, const float* gla_norm) {
;     ...
;         const float rstd = rsqrtf((RED[wave * 16 + lr] + RED[(wave ^ 4) * 16 + lr]) * (1.f / 128.f) + EPS);
;         const size_t m = m0 + 16 * it + lr;
; #pragma unroll
;         for (int v4 = 0; v4 < 4; ++v4) { const int vcol = 16 * (4 * vh + v4) + 4 * lq; const v2u rr = rr4[v4]; const f32x4 g = gn4[v4];
;             v2u o; o.x = pk2(acc[v4][0] * rstd * g.x * bflo(rr.x), acc[v4][1] * rstd * g.y * bfhi(rr.x)); o.y = pk2(acc[v4][2] * rstd * g.z * bflo(rr.y), acc[v4][3] * rstd * g.w * bfhi(rr.y));
;             *(v2u*)(OMIX + m * 1024 + h * 128 + vcol) = o; }
.LBB0_759:
	s_or_b64 exec, exec, s[0:1]
	s_add_i32 s0, 0, 0x14c00
	s_add_i32 s1, s0, s3
	s_waitcnt lgkmcnt(0)
	v_bitop3_b32 v35, s4, 64, v116 bitop3:0x36
	v_lshl_add_u32 v34, v116, 2, s1
	v_lshl_add_u32 v35, v35, 2, s0
	s_barrier
	ds_read_b32 v34, v34
	ds_read_b32 v35, v35
	v_lshlrev_b64 v[36:37], 11, v[110:111]
	v_lshl_add_u64 v[36:37], s[40:41], 0, v[36:37]
	s_add_i32 s0, s82, 0x100
	s_cmpk_gt_i32 s82, 0x2ff
	s_waitcnt lgkmcnt(0)
	v_add_f32_e32 v34, v34, v35
	v_fmamk_f32 v34, v34, 0x3c000000, v112
	v_mul_f32_e32 v35, 0x4b800000, v34
	v_cmp_gt_f32_e32 vcc, s81, v34
	s_mov_b32 s82, s0
	s_nop 0
	v_cndmask_b32_e32 v34, v34, v35, vcc
	v_rsq_f32_e32 v34, v34
	s_nop 0
	v_mul_f32_e32 v35, 0x45800000, v34
	v_cndmask_b32_e32 v34, v34, v35, vcc
	v_pk_mul_f32 v[30:31], v[30:31], v[34:35] op_sel_hi:[1,0]
	s_waitcnt vmcnt(6)
	v_pk_mul_f32 v[14:15], v[14:15], v[30:31]
	v_lshlrev_b32_e32 v30, 16, v108
	v_and_b32_e32 v31, 0xffff0000, v108
	v_pk_mul_f32 v[14:15], v[14:15], v[30:31]
	v_pk_mul_f32 v[30:31], v[32:33], v[34:35] op_sel_hi:[1,0]
	v_cvt_pk_bf16_f32 v148, v14, v15
	v_pk_mul_f32 v[16:17], v[16:17], v[30:31]
	v_lshlrev_b32_e32 v30, 16, v109
	v_and_b32_e32 v31, 0xffff0000, v109
	v_pk_mul_f32 v[16:17], v[16:17], v[30:31]
	s_nop 0
	v_cvt_pk_bf16_f32 v149, v16, v17
	v_lshl_add_u64 v[16:17], v[106:107], 1, v[36:37]
	v_pk_mul_f32 v[14:15], v[26:27], v[34:35] op_sel_hi:[1,0]
	s_waitcnt vmcnt(3)
	v_pk_mul_f32 v[10:11], v[10:11], v[14:15]
	v_lshlrev_b32_e32 v14, 16, v104
	v_and_b32_e32 v15, 0xffff0000, v104
	v_pk_mul_f32 v[10:11], v[10:11], v[14:15]
	v_pk_mul_f32 v[14:15], v[28:29], v[34:35] op_sel_hi:[1,0]
	v_cvt_pk_bf16_f32 v150, v10, v11
	v_pk_mul_f32 v[12:13], v[12:13], v[14:15]
	v_lshlrev_b32_e32 v14, 16, v105
	v_and_b32_e32 v15, 0xffff0000, v105
	v_pk_mul_f32 v[12:13], v[12:13], v[14:15]
	s_nop 0
	v_cvt_pk_bf16_f32 v151, v12, v13
	v_lshl_add_u64 v[12:13], v[102:103], 1, v[36:37]
	v_and_b32_e32 v152, 4, v106
	v_mul_u32_u24_e32 v152, 6, v152
	v_mov_b32_e32 v153, 0
	v_permlane16_swap_b32 v148, v150
	v_permlane16_swap_b32 v149, v151
	v_lshl_add_u64 v[16:17], v[16:17], 0, v[152:153]
	global_store_dwordx4 v[16:17], v[148:151], off sc1
	v_pk_mul_f32 v[10:11], v[22:23], v[34:35] op_sel_hi:[1,0]
	s_waitcnt vmcnt(3)
	v_pk_mul_f32 v[6:7], v[6:7], v[10:11]
	v_lshlrev_b32_e32 v10, 16, v100
	v_and_b32_e32 v11, 0xffff0000, v100
	v_pk_mul_f32 v[6:7], v[6:7], v[10:11]
	v_pk_mul_f32 v[10:11], v[24:25], v[34:35] op_sel_hi:[1,0]
	v_cvt_pk_bf16_f32 v154, v6, v7
	v_pk_mul_f32 v[8:9], v[8:9], v[10:11]
	v_lshlrev_b32_e32 v10, 16, v101
	v_and_b32_e32 v11, 0xffff0000, v101
	v_pk_mul_f32 v[8:9], v[8:9], v[10:11]
	s_nop 0
	v_cvt_pk_bf16_f32 v155, v8, v9
	v_pk_mul_f32 v[6:7], v[18:19], v[34:35] op_sel_hi:[1,0]
	s_waitcnt vmcnt(1)
	v_pk_mul_f32 v[2:3], v[2:3], v[6:7]
	v_lshlrev_b32_e32 v6, 16, v98
	v_and_b32_e32 v7, 0xffff0000, v98
	v_pk_mul_f32 v[2:3], v[2:3], v[6:7]
	v_pk_mul_f32 v[6:7], v[20:21], v[34:35] op_sel_hi:[1,0]
	v_cvt_pk_bf16_f32 v156, v2, v3
	v_pk_mul_f32 v[4:5], v[4:5], v[6:7]
	v_lshlrev_b32_e32 v6, 16, v99
	v_and_b32_e32 v7, 0xffff0000, v99
	v_pk_mul_f32 v[4:5], v[4:5], v[6:7]
	s_nop 0
	v_cvt_pk_bf16_f32 v157, v4, v5
	v_lshl_add_u64 v[4:5], v[96:97], 1, v[36:37]
	s_nop 1
	v_permlane16_swap_b32 v154, v156
	v_permlane16_swap_b32 v155, v157
	v_lshl_add_u64 v[12:13], v[12:13], 0, v[152:153]
	global_store_dwordx4 v[12:13], v[154:157], off offset:64 sc1
	s_barrier
	s_cbranch_scc1 .LBB0_786

; __device__ __forceinline__ unsigned pk2(float lo, float hi) { const f32x2cv v = {lo, hi}; const bf16x2cv b = __builtin_convertvector(v, bf16x2cv); return __builtin_bit_cast(unsigned, b); }
; template <int PASS>
; __device__ __forceinline__ void ssd_unit(LAS unsigned char* lds, int ch, int g, const bf16* PROJ, const bf16* XBC, const float* At, const float* DTt, bf16* STS, float* DECS, bf16* OMIX,
;                                          const float* d_skip, const float* ssd_norm) {
;     ...
;         __syncthreads();
; #pragma unroll
;         for (int i2 = 0; i2 < 2; ++i2) { float t = 0.f;
; #pragma unroll
;             for (int h4 = 0; h4 < 4; ++h4) t += RED[(2 * h4 + ih) * 32 + i2 * 16 + lr];
;             rs2[i2] = rsqrtf(t * (1.f / 256.f) + EPS); }
; #pragma unroll
;         for (int i2 = 0; i2 < 2; ++i2) { const size_t m = m0 + 16 * (2 * ih + i2) + lr;
; #pragma unroll
;             for (int pt = 0; pt < 4; ++pt) { const int col = 256 * g + 64 * hl + 16 * pt + 4 * lq; const f32x4 gn = gn8[pt];
;                 v2u o; o.x = pk2(yv[i2][pt][0] * rs2[i2] * gn.x, yv[i2][pt][1] * rs2[i2] * gn.y); o.y = pk2(yv[i2][pt][2] * rs2[i2] * gn.z, yv[i2][pt][3] * rs2[i2] * gn.w);
;                 *(v2u*)(OMIX + m * 1024 + 512 + col) = o; } }
.LBB0_788:
	s_or_b64 exec, exec, s[0:1]
	s_lshl_b32 s0, s12, 7
	s_add_i32 s0, s0, 0
	v_lshl_add_u32 v32, v140, 2, s0
	v_add_u32_e32 v38, 0x1a400, v32
	s_waitcnt lgkmcnt(0)
	s_barrier
	ds_read2_b32 v[32:33], v38 offset1:16
	ds_read2_b32 v[34:35], v38 offset0:64 offset1:80
	ds_read2_b32 v[36:37], v38 offset0:128 offset1:144
	ds_read2_b32 v[38:39], v38 offset0:192 offset1:208
	s_add_i32 s0, s36, s35
	s_waitcnt lgkmcnt(3)
	v_mov_b32_e32 v40, v33
	v_mov_b32_e32 v41, v32
	v_pk_add_f32 v[32:33], v[40:41], 0 op_sel_hi:[1,0]
	s_waitcnt lgkmcnt(2)
	v_mov_b32_e32 v40, v35
	v_mov_b32_e32 v41, v34
	v_pk_add_f32 v[32:33], v[32:33], v[40:41]
	s_waitcnt lgkmcnt(1)
	v_mov_b32_e32 v34, v37
	v_mov_b32_e32 v35, v36
	v_pk_add_f32 v[32:33], v[32:33], v[34:35]
	s_waitcnt lgkmcnt(0)
	v_mov_b32_e32 v34, v39
	v_mov_b32_e32 v35, v38
	v_pk_add_f32 v[32:33], v[32:33], v[34:35]
	v_or_b32_e32 v36, s0, v110
	v_pk_fma_f32 v[32:33], v[32:33], s[30:31], v[116:117] op_sel_hi:[1,0,0]
	v_lshlrev_b64 v[38:39], 11, v[120:121]
	v_mul_f32_e32 v34, 0x4b800000, v33
	v_cmp_gt_f32_e32 vcc, s62, v33
	v_cmp_gt_f32_e64 s[4:5], s62, v32
	v_ashrrev_i32_e32 v37, 31, v36
	v_cndmask_b32_e32 v33, v33, v34, vcc
	v_mul_f32_e32 v34, 0x4b800000, v32
	v_rsq_f32_e32 v33, v33
	v_cndmask_b32_e64 v32, v32, v34, s[4:5]
	v_rsq_f32_e32 v34, v32
	v_lshl_add_u64 v[38:39], s[76:77], 0, v[38:39]
	v_mul_f32_e32 v32, 0x45800000, v33
	v_cndmask_b32_e32 v32, v33, v32, vcc
	v_mul_f32_e32 v33, 0x45800000, v34
	v_pk_mul_f32 v[40:41], v[82:83], v[32:33] op_sel_hi:[1,0]
	v_pk_mul_f32 v[44:45], v[84:85], v[32:33] op_sel_hi:[1,0]
	s_waitcnt vmcnt(3)
	v_pk_mul_f32 v[40:41], v[14:15], v[40:41]
	v_pk_mul_f32 v[44:45], v[16:17], v[44:45]
	v_lshlrev_b64 v[36:37], 1, v[36:37]
	v_cvt_pk_bf16_f32 v208, v40, v41
	v_cvt_pk_bf16_f32 v209, v44, v45
	v_lshl_add_u64 v[38:39], v[38:39], 0, v[36:37]
	v_pk_mul_f32 v[40:41], v[86:87], v[32:33] op_sel_hi:[1,0]
	v_pk_mul_f32 v[44:45], v[88:89], v[32:33] op_sel_hi:[1,0]
	s_waitcnt vmcnt(2)
	v_pk_mul_f32 v[40:41], v[10:11], v[40:41]
	v_pk_mul_f32 v[44:45], v[12:13], v[44:45]
	v_cvt_pk_bf16_f32 v210, v40, v41
	v_cvt_pk_bf16_f32 v211, v44, v45
	v_and_b32_e32 v224, 8, v36
	v_lshl_add_u32 v224, v224, 1, v224
	v_mov_b32_e32 v225, 0
	v_permlane16_swap_b32 v208, v210
	v_permlane16_swap_b32 v209, v211
	v_lshl_add_u64 v[38:39], v[38:39], 0, v[224:225]
	global_store_dwordx4 v[38:39], v[208:211], off offset:1024 sc1
	v_pk_mul_f32 v[40:41], v[90:91], v[32:33] op_sel_hi:[1,0]
	v_pk_mul_f32 v[44:45], v[92:93], v[32:33] op_sel_hi:[1,0]
	s_waitcnt vmcnt(2)
	v_pk_mul_f32 v[40:41], v[6:7], v[40:41]
	v_pk_mul_f32 v[44:45], v[8:9], v[44:45]
	v_cvt_pk_bf16_f32 v212, v40, v41
	v_cvt_pk_bf16_f32 v213, v44, v45
	v_cndmask_b32_e64 v34, v34, v33, s[4:5]
	v_pk_mul_f32 v[40:41], v[94:95], v[32:33] op_sel_hi:[1,0]
	v_pk_mul_f32 v[32:33], v[96:97], v[32:33] op_sel_hi:[1,0]
	s_waitcnt vmcnt(1)
	v_pk_mul_f32 v[40:41], v[2:3], v[40:41]
	v_pk_mul_f32 v[32:33], v[4:5], v[32:33]
	v_mov_b32_e32 v119, v121
	v_cvt_pk_bf16_f32 v214, v40, v41
	v_cvt_pk_bf16_f32 v215, v32, v33
	s_nop 1
	v_permlane16_swap_b32 v212, v214
	v_permlane16_swap_b32 v213, v215
	global_store_dwordx4 v[38:39], v[212:215], off offset:1088 sc1
	v_lshlrev_b64 v[32:33], 11, v[118:119]
	v_pk_mul_f32 v[38:39], v[42:43], v[34:35] op_sel_hi:[1,0]
	v_pk_mul_f32 v[30:31], v[30:31], v[34:35] op_sel_hi:[1,0]
	v_lshl_add_u64 v[32:33], s[76:77], 0, v[32:33]
	v_pk_mul_f32 v[14:15], v[14:15], v[38:39]
	v_pk_mul_f32 v[16:17], v[16:17], v[30:31]
	v_cvt_pk_bf16_f32 v216, v14, v15
	v_cvt_pk_bf16_f32 v217, v16, v17
	v_lshl_add_u64 v[16:17], v[32:33], 0, v[36:37]
	v_pk_mul_f32 v[14:15], v[22:23], v[34:35] op_sel_hi:[1,0]
	s_add_i32 s0, s63, 0x100
	v_pk_mul_f32 v[10:11], v[10:11], v[14:15]
	v_pk_mul_f32 v[14:15], v[18:19], v[34:35] op_sel_hi:[1,0]
	v_cvt_pk_bf16_f32 v218, v10, v11
	v_pk_mul_f32 v[12:13], v[12:13], v[14:15]
	s_cmpk_gt_i32 s63, 0xff
	v_cvt_pk_bf16_f32 v219, v12, v13
	s_nop 1
	v_permlane16_swap_b32 v216, v218
	v_permlane16_swap_b32 v217, v219
	v_lshl_add_u64 v[16:17], v[16:17], 0, v[224:225]
	global_store_dwordx4 v[16:17], v[216:219], off offset:1024 sc1
	v_pk_mul_f32 v[10:11], v[20:21], v[34:35] op_sel_hi:[1,0]
	s_mov_b32 s63, s0
	v_pk_mul_f32 v[6:7], v[6:7], v[10:11]
	v_pk_mul_f32 v[10:11], v[24:25], v[34:35] op_sel_hi:[1,0]
	v_cvt_pk_bf16_f32 v220, v6, v7
	v_pk_mul_f32 v[8:9], v[8:9], v[10:11]
	s_nop 0
	v_cvt_pk_bf16_f32 v221, v8, v9
	v_pk_mul_f32 v[6:7], v[26:27], v[34:35] op_sel_hi:[1,0]
	s_nop 0
	v_pk_mul_f32 v[2:3], v[2:3], v[6:7]
	v_pk_mul_f32 v[6:7], v[28:29], v[34:35] op_sel_hi:[1,0]
	v_cvt_pk_bf16_f32 v222, v2, v3
	v_pk_mul_f32 v[4:5], v[4:5], v[6:7]
	s_nop 0
	v_cvt_pk_bf16_f32 v223, v4, v5
	s_nop 1
	v_permlane16_swap_b32 v220, v222
	v_permlane16_swap_b32 v221, v223
	global_store_dwordx4 v[16:17], v[220:223], off offset:1088 sc1
	s_barrier
	s_cbranch_scc1 .LBB0_959
